# s30 plus a device-scope L1 invalidate at the XCD-local barrier after sub4 (hn buffer aliases xn read in sub2)
# baseline (speedup 1.0000x reference)
.Llb_do:
	s_waitcnt vmcnt(0) lgkmcnt(0)
	s_barrier
	v_readlane_b32 s8, v255, 52
	s_add_i32 s8, s8, 1
	v_writelane_b32 v255, s8, 52
	s_mov_b64 s[10:11], exec
	v_readlane_b32 s2, v254, 0
	v_readlane_b32 s3, v254, 1
	s_and_b64 s[2:3], s[10:11], s[2:3]
	s_mov_b64 exec, s[2:3]
	s_cbranch_execz .Llb_done
	s_and_b32 s9, s82, 7
	s_lshl_b32 s9, s9, 8
	s_addk_i32 s9, 0x480
	v_mov_b32_e32 v0, s9
	v_mov_b32_e32 v1, 1
	global_atomic_add v2, v0, v1, s[4:5] sc0
	s_cmp_eq_u32 s99, 4
	s_cbranch_scc1 .Llb_i1
	buffer_inv sc0
	s_branch .Llb_i2

.Llb_i2:
	v_add_u32_e32 v0, 0x2000, v0
	s_waitcnt vmcnt(0)
	v_readfirstlane_b32 s9, v2
	s_add_i32 s9, s9, 1
	s_lshl_b32 s13, s8, 6
	s_cmp_eq_u32 s9, s13
	s_cbranch_scc0 .Llb_wait
	global_atomic_add v0, v1, s[4:5]
	s_branch .Llb_done
